# scan producer: counted vmcnt waits on top of the 16-byte gate/OG accesses (each half waits only for the previous half's gate loads and older; newest 28 operand loads stay in flight)
# speedup vs baseline: 1.2514x; 1.0028x over previous
.LBB0_295:
	ds_read_b128 v[130:133], v188
	ds_read_b128 v[134:137], v188 offset:16
	ds_read_b128 v[138:141], v188 offset:256
	ds_read_b128 v[142:145], v188 offset:272
	ds_read_b128 v[146:149], v188 offset:512
	ds_read_b128 v[150:153], v188 offset:528
	ds_read_b128 v[154:157], v188 offset:768
	ds_read_b128 v[166:169], v188 offset:784
	s_sub_i32 s0, s8, s25
	v_cmp_gt_i32_e32 vcc, s26, v175
	s_min_i32 s1, s24, s20
	s_lshl_b32 s1, s1, 5
	s_sub_i32 s25, s17, s1
	v_lshlrev_b32_e32 v172, 16, v126
	v_and_b32_e32 v173, 0xffff0000, v126
	s_cmp_gt_i32 s25, 31
	s_waitcnt lgkmcnt(6)
	v_mul_f32_e32 v238, v130, v130
	v_mul_f32_e32 v239, v131, v131
	v_mul_f32_e32 v240, v132, v132
	v_mul_f32_e32 v241, v133, v133
	v_fmac_f32_e32 v238, v134, v134
	v_fmac_f32_e32 v239, v135, v135
	v_fmac_f32_e32 v240, v136, v136
	v_fmac_f32_e32 v241, v137, v137
	s_waitcnt lgkmcnt(4)
	v_fmac_f32_e32 v238, v138, v138
	v_fmac_f32_e32 v239, v139, v139
	v_fmac_f32_e32 v240, v140, v140
	v_fmac_f32_e32 v241, v141, v141
	v_fmac_f32_e32 v238, v142, v142
	v_fmac_f32_e32 v239, v143, v143
	v_fmac_f32_e32 v240, v144, v144
	v_fmac_f32_e32 v241, v145, v145
	s_waitcnt lgkmcnt(2)
	v_fmac_f32_e32 v238, v146, v146
	v_fmac_f32_e32 v239, v147, v147
	v_fmac_f32_e32 v240, v148, v148
	v_fmac_f32_e32 v241, v149, v149
	v_fmac_f32_e32 v238, v150, v150
	v_fmac_f32_e32 v239, v151, v151
	v_fmac_f32_e32 v240, v152, v152
	v_fmac_f32_e32 v241, v153, v153
	s_waitcnt lgkmcnt(0)
	v_fmac_f32_e32 v238, v154, v154
	v_fmac_f32_e32 v239, v155, v155
	v_fmac_f32_e32 v240, v156, v156
	v_fmac_f32_e32 v241, v157, v157
	v_fmac_f32_e32 v238, v166, v166
	v_fmac_f32_e32 v239, v167, v167
	v_fmac_f32_e32 v240, v168, v168
	v_fmac_f32_e32 v241, v169, v169
	v_add_f32_e32 v238, v238, v239
	v_add_f32_e32 v240, v240, v241
	v_add_f32_e32 v158, v238, v240
	s_nop 1
	v_add_f32_dpp v158, v158, v158 quad_perm:[1,0,3,2] row_mask:0xf bank_mask:0xf
	s_nop 1
	v_add_f32_dpp v158, v158, v158 quad_perm:[2,3,0,1] row_mask:0xf bank_mask:0xf
	s_nop 1
	v_add_f32_dpp v158, v158, v158 row_half_mirror row_mask:0xf bank_mask:0xf
	v_fmamk_f32 v158, v158, 0x3b800000, v206
	v_rsq_f32_e32 v158, v158
	v_mov_b32_e32 v159, s0
	v_cndmask_b32_e32 v159, v210, v159, vcc
	v_add_u32_e32 v170, v159, v175
	v_ashrrev_i32_e32 v171, 31, v170
	v_lshlrev_b64 v[170:171], 13, v[170:171]
	v_lshl_add_u64 v[170:171], v[74:75], 0, v[170:171]
	v_pk_mul_f32 v[130:131], v[130:131], v[158:159] op_sel_hi:[1,0]
	v_lshlrev_b32_e32 v238, 16, v80
	v_and_b32_e32 v239, 0xffff0000, v80
	v_pk_mul_f32 v[130:131], v[130:131], v[238:239]
	v_cvt_pk_bf16_f32 v80, v130, v131
	v_pk_mul_f32 v[132:133], v[132:133], v[158:159] op_sel_hi:[1,0]
	v_lshlrev_b32_e32 v238, 16, v81
	v_and_b32_e32 v239, 0xffff0000, v81
	v_pk_mul_f32 v[132:133], v[132:133], v[238:239]
	v_cvt_pk_bf16_f32 v81, v132, v133
	v_pk_mul_f32 v[134:135], v[134:135], v[158:159] op_sel_hi:[1,0]
	v_lshlrev_b32_e32 v238, 16, v82
	v_and_b32_e32 v239, 0xffff0000, v82
	v_pk_mul_f32 v[134:135], v[134:135], v[238:239]
	v_cvt_pk_bf16_f32 v82, v134, v135
	v_pk_mul_f32 v[136:137], v[136:137], v[158:159] op_sel_hi:[1,0]
	v_lshlrev_b32_e32 v238, 16, v83
	v_and_b32_e32 v239, 0xffff0000, v83
	v_pk_mul_f32 v[136:137], v[136:137], v[238:239]
	v_cvt_pk_bf16_f32 v83, v136, v137
	global_store_dwordx4 v[170:171], v[80:83], off
	v_pk_mul_f32 v[138:139], v[138:139], v[158:159] op_sel_hi:[1,0]
	v_lshlrev_b32_e32 v238, 16, v84
	v_and_b32_e32 v239, 0xffff0000, v84
	v_pk_mul_f32 v[138:139], v[138:139], v[238:239]
	v_cvt_pk_bf16_f32 v84, v138, v139
	v_pk_mul_f32 v[140:141], v[140:141], v[158:159] op_sel_hi:[1,0]
	v_lshlrev_b32_e32 v238, 16, v85
	v_and_b32_e32 v239, 0xffff0000, v85
	v_pk_mul_f32 v[140:141], v[140:141], v[238:239]
	v_cvt_pk_bf16_f32 v85, v140, v141
	v_pk_mul_f32 v[142:143], v[142:143], v[158:159] op_sel_hi:[1,0]
	v_lshlrev_b32_e32 v238, 16, v86
	v_and_b32_e32 v239, 0xffff0000, v86
	v_pk_mul_f32 v[142:143], v[142:143], v[238:239]
	v_cvt_pk_bf16_f32 v86, v142, v143
	v_pk_mul_f32 v[144:145], v[144:145], v[158:159] op_sel_hi:[1,0]
	v_lshlrev_b32_e32 v238, 16, v87
	v_and_b32_e32 v239, 0xffff0000, v87
	v_pk_mul_f32 v[144:145], v[144:145], v[238:239]
	v_cvt_pk_bf16_f32 v87, v144, v145
	global_store_dwordx4 v[170:171], v[84:87], off offset:128
	v_pk_mul_f32 v[146:147], v[146:147], v[158:159] op_sel_hi:[1,0]
	v_lshlrev_b32_e32 v238, 16, v92
	v_and_b32_e32 v239, 0xffff0000, v92
	v_pk_mul_f32 v[146:147], v[146:147], v[238:239]
	v_cvt_pk_bf16_f32 v92, v146, v147
	v_pk_mul_f32 v[148:149], v[148:149], v[158:159] op_sel_hi:[1,0]
	v_lshlrev_b32_e32 v238, 16, v93
	v_and_b32_e32 v239, 0xffff0000, v93
	v_pk_mul_f32 v[148:149], v[148:149], v[238:239]
	v_cvt_pk_bf16_f32 v93, v148, v149
	v_pk_mul_f32 v[150:151], v[150:151], v[158:159] op_sel_hi:[1,0]
	v_lshlrev_b32_e32 v238, 16, v94
	v_and_b32_e32 v239, 0xffff0000, v94
	v_pk_mul_f32 v[150:151], v[150:151], v[238:239]
	v_cvt_pk_bf16_f32 v94, v150, v151
	v_pk_mul_f32 v[152:153], v[152:153], v[158:159] op_sel_hi:[1,0]
	v_lshlrev_b32_e32 v238, 16, v95
	v_and_b32_e32 v239, 0xffff0000, v95
	v_pk_mul_f32 v[152:153], v[152:153], v[238:239]
	v_cvt_pk_bf16_f32 v95, v152, v153
	global_store_dwordx4 v[170:171], v[92:95], off offset:256
	v_pk_mul_f32 v[154:155], v[154:155], v[158:159] op_sel_hi:[1,0]
	v_lshlrev_b32_e32 v238, 16, v96
	v_and_b32_e32 v239, 0xffff0000, v96
	v_pk_mul_f32 v[154:155], v[154:155], v[238:239]
	v_cvt_pk_bf16_f32 v96, v154, v155
	v_pk_mul_f32 v[156:157], v[156:157], v[158:159] op_sel_hi:[1,0]
	v_lshlrev_b32_e32 v238, 16, v97
	v_and_b32_e32 v239, 0xffff0000, v97
	v_pk_mul_f32 v[156:157], v[156:157], v[238:239]
	v_cvt_pk_bf16_f32 v97, v156, v157
	v_pk_mul_f32 v[166:167], v[166:167], v[158:159] op_sel_hi:[1,0]
	v_lshlrev_b32_e32 v238, 16, v98
	v_and_b32_e32 v239, 0xffff0000, v98
	v_pk_mul_f32 v[166:167], v[166:167], v[238:239]
	v_cvt_pk_bf16_f32 v98, v166, v167
	v_pk_mul_f32 v[168:169], v[168:169], v[158:159] op_sel_hi:[1,0]
	v_lshlrev_b32_e32 v238, 16, v99
	v_and_b32_e32 v239, 0xffff0000, v99
	v_pk_mul_f32 v[168:169], v[168:169], v[238:239]
	v_cvt_pk_bf16_f32 v99, v168, v169
	global_store_dwordx4 v[170:171], v[96:99], off offset:384
	s_waitcnt vmcnt(32)
	v_lshlrev_b32_e32 v168, 16, v232
	v_add_u32_e32 v238, s1, v217
	v_ashrrev_i32_e32 v239, 31, v238
	v_lshlrev_b64 v[238:239], 13, v[238:239]
	v_lshl_add_u64 v[238:239], v[78:79], 0, v[238:239]
	global_load_dwordx4 v[80:83], v[238:239], off
	global_load_dwordx4 v[84:87], v[238:239], off offset:128
	global_load_dwordx4 v[92:95], v[238:239], off offset:256
	global_load_dwordx4 v[96:99], v[238:239], off offset:384
	s_mov_b64 s[0:1], -1
	v_lshlrev_b32_e32 v170, 16, v234
	v_lshlrev_b32_e32 v166, 16, v231
	v_lshlrev_b32_e32 v158, 16, v229
	s_cbranch_scc1 .LBB0_297
	s_min_i32 s0, s25, 32
	v_add_f32_e32 v130, 0, v106
	v_cmp_gt_i32_e32 vcc, s0, v176
	v_and_b32_e32 v132, 0xffff0000, v235
	v_and_b32_e32 v134, 0xffff0000, v234
	v_cndmask_b32_e32 v136, 0, v130, vcc
	v_add_f32_e32 v130, 0, v107
	v_cndmask_b32_e32 v139, 0, v130, vcc
	v_lshlrev_b32_e32 v130, 16, v233
	v_cndmask_b32_e32 v131, 0, v130, vcc
	v_and_b32_e32 v130, 0xffff0000, v233
	v_cndmask_b32_e32 v241, 0, v130, vcc
	v_cmp_gt_i32_e32 vcc, s0, v1
	v_lshlrev_b32_e32 v130, 16, v235
	v_and_b32_e32 v135, 0xffff0000, v232
	v_cndmask_b32_e32 v133, 0, v102, vcc
	v_add_f32_e32 v138, v136, v133
	v_cndmask_b32_e32 v239, 0, v130, vcc
	v_cndmask_b32_e32 v240, 0, v132, vcc
	v_cndmask_b32_e32 v133, 0, v103, vcc
	v_cmp_gt_i32_e32 vcc, s0, v40
	v_and_b32_e32 v137, 0xffff0000, v231
	v_and_b32_e32 v140, 0xffff0000, v229
	v_cndmask_b32_e32 v132, 0, v118, vcc
	v_cmp_gt_i32_e32 vcc, s0, v41
	v_pk_add_f32 v[146:147], v[132:133], v[138:139]
	v_lshlrev_b32_e32 v159, 16, v236
	v_cndmask_b32_e32 v157, 0, v134, vcc
	v_cndmask_b32_e32 v156, 0, v170, vcc
	v_cndmask_b32_e32 v133, 0, v119, vcc
	v_cmp_gt_i32_e32 vcc, s0, v54
	v_lshlrev_b32_e32 v162, 16, v237
	v_and_b32_e32 v163, 0xffff0000, v236
	v_cndmask_b32_e32 v132, 0, v114, vcc
	v_cmp_gt_i32_e32 vcc, s0, v3
	v_pk_add_f32 v[148:149], v[132:133], v[146:147]
	s_nop 0
	v_cndmask_b32_e32 v155, 0, v135, vcc
	v_cndmask_b32_e32 v154, 0, v168, vcc
	v_cndmask_b32_e32 v133, 0, v115, vcc
	v_cmp_gt_i32_e32 vcc, s0, v52
	s_nop 1
	v_cndmask_b32_e32 v132, 0, v100, vcc
	v_cmp_gt_i32_e32 vcc, s0, v43
	v_pk_add_f32 v[142:143], v[132:133], v[148:149]
	s_nop 0
	v_cndmask_b32_e32 v153, 0, v137, vcc
	v_cndmask_b32_e32 v152, 0, v166, vcc
	v_cndmask_b32_e32 v133, 0, v101, vcc
	v_cmp_gt_i32_e32 vcc, s0, v42
	s_nop 1
	v_cndmask_b32_e32 v132, 0, v90, vcc
	v_cmp_gt_i32_e32 vcc, s0, v51
	v_pk_add_f32 v[144:145], v[132:133], v[142:143]
	s_nop 0
	v_cndmask_b32_e32 v151, 0, v140, vcc
	v_cndmask_b32_e32 v150, 0, v158, vcc
	v_cndmask_b32_e32 v133, 0, v91, vcc
	v_cmp_gt_i32_e32 vcc, s0, v50
	s_nop 1
	v_cndmask_b32_e32 v132, 0, v108, vcc
	v_cmp_gt_i32_e32 vcc, s0, v45
	v_cmp_gt_i32_e64 s[0:1], s0, v44
	v_pk_add_f32 v[140:141], v[132:133], v[144:145]
	v_cndmask_b32_e32 v133, 0, v109, vcc
	v_cndmask_b32_e64 v132, 0, v128, s[0:1]
	v_cndmask_b32_e32 v130, 0, v159, vcc
	v_pk_add_f32 v[134:135], v[132:133], v[140:141]
	v_cndmask_b32_e64 v132, 0, v129, s[0:1]
	v_and_b32_e32 v159, 0xffff0000, v237
	v_add_f32_e32 v137, v132, v135
	v_cndmask_b32_e32 v133, 0, v163, vcc
	v_cndmask_b32_e64 v132, 0, v162, s[0:1]
	v_cndmask_b32_e64 v238, 0, v159, s[0:1]
	s_mov_b64 s[0:1], 0

.LBB0_305:
	ds_read_b128 v[130:133], v188 offset:33280
	ds_read_b128 v[134:137], v188 offset:33296
	ds_read_b128 v[138:141], v188 offset:33536
	ds_read_b128 v[142:145], v188 offset:33552
	ds_read_b128 v[146:149], v188 offset:33792
	ds_read_b128 v[150:153], v188 offset:33808
	ds_read_b128 v[154:157], v188 offset:34048
	ds_read_b128 v[166:169], v188 offset:34064
	s_sub_i32 s0, s21, s0
	v_cmp_gt_i32_e32 vcc, s1, v175
	s_add_i32 s10, s24, 1
	s_min_i32 s10, s10, s20
	v_lshlrev_b32_e32 v170, 16, v124
	v_and_b32_e32 v171, 0xffff0000, v124
	s_lshl_b32 s10, s10, 5
	s_waitcnt lgkmcnt(6)
	v_mul_f32_e32 v238, v130, v130
	v_mul_f32_e32 v239, v131, v131
	v_mul_f32_e32 v240, v132, v132
	v_mul_f32_e32 v241, v133, v133
	v_fmac_f32_e32 v238, v134, v134
	v_fmac_f32_e32 v239, v135, v135
	v_fmac_f32_e32 v240, v136, v136
	v_fmac_f32_e32 v241, v137, v137
	s_waitcnt lgkmcnt(4)
	v_fmac_f32_e32 v238, v138, v138
	v_fmac_f32_e32 v239, v139, v139
	v_fmac_f32_e32 v240, v140, v140
	v_fmac_f32_e32 v241, v141, v141
	v_fmac_f32_e32 v238, v142, v142
	v_fmac_f32_e32 v239, v143, v143
	v_fmac_f32_e32 v240, v144, v144
	v_fmac_f32_e32 v241, v145, v145
	s_waitcnt lgkmcnt(2)
	v_fmac_f32_e32 v238, v146, v146
	v_fmac_f32_e32 v239, v147, v147
	v_fmac_f32_e32 v240, v148, v148
	v_fmac_f32_e32 v241, v149, v149
	v_fmac_f32_e32 v238, v150, v150
	v_fmac_f32_e32 v239, v151, v151
	v_fmac_f32_e32 v240, v152, v152
	v_fmac_f32_e32 v241, v153, v153
	s_waitcnt lgkmcnt(0)
	v_fmac_f32_e32 v238, v154, v154
	v_fmac_f32_e32 v239, v155, v155
	v_fmac_f32_e32 v240, v156, v156
	v_fmac_f32_e32 v241, v157, v157
	v_fmac_f32_e32 v238, v166, v166
	v_fmac_f32_e32 v239, v167, v167
	v_fmac_f32_e32 v240, v168, v168
	v_fmac_f32_e32 v241, v169, v169
	v_add_f32_e32 v238, v238, v239
	v_add_f32_e32 v240, v240, v241
	v_add_f32_e32 v158, v238, v240
	s_nop 1
	v_add_f32_dpp v158, v158, v158 quad_perm:[1,0,3,2] row_mask:0xf bank_mask:0xf
	s_nop 1
	v_add_f32_dpp v158, v158, v158 quad_perm:[2,3,0,1] row_mask:0xf bank_mask:0xf
	s_nop 1
	v_add_f32_dpp v158, v158, v158 row_half_mirror row_mask:0xf bank_mask:0xf
	v_fmamk_f32 v158, v158, 0x3b800000, v206
	v_rsq_f32_e32 v158, v158
	v_mov_b32_e32 v159, s0
	v_cndmask_b32_e32 v159, v210, v159, vcc
	v_add_u32_e32 v162, v159, v175
	v_ashrrev_i32_e32 v163, 31, v162
	v_lshlrev_b64 v[162:163], 13, v[162:163]
	v_lshl_add_u64 v[162:163], v[74:75], 0, v[162:163]
	s_mov_b64 s[0:1], -1
	v_pk_mul_f32 v[130:131], v[130:131], v[158:159] op_sel_hi:[1,0]
	v_lshlrev_b32_e32 v238, 16, v120
	v_and_b32_e32 v239, 0xffff0000, v120
	v_pk_mul_f32 v[130:131], v[130:131], v[238:239]
	v_cvt_pk_bf16_f32 v120, v130, v131
	v_pk_mul_f32 v[132:133], v[132:133], v[158:159] op_sel_hi:[1,0]
	v_lshlrev_b32_e32 v238, 16, v121
	v_and_b32_e32 v239, 0xffff0000, v121
	v_pk_mul_f32 v[132:133], v[132:133], v[238:239]
	v_cvt_pk_bf16_f32 v121, v132, v133
	v_pk_mul_f32 v[134:135], v[134:135], v[158:159] op_sel_hi:[1,0]
	v_lshlrev_b32_e32 v238, 16, v122
	v_and_b32_e32 v239, 0xffff0000, v122
	v_pk_mul_f32 v[134:135], v[134:135], v[238:239]
	v_cvt_pk_bf16_f32 v122, v134, v135
	v_pk_mul_f32 v[136:137], v[136:137], v[158:159] op_sel_hi:[1,0]
	v_lshlrev_b32_e32 v238, 16, v123
	v_and_b32_e32 v239, 0xffff0000, v123
	v_pk_mul_f32 v[136:137], v[136:137], v[238:239]
	v_cvt_pk_bf16_f32 v123, v136, v137
	global_store_dwordx4 v[162:163], v[120:123], off
	v_pk_mul_f32 v[138:139], v[138:139], v[158:159] op_sel_hi:[1,0]
	v_lshlrev_b32_e32 v238, 16, v124
	v_and_b32_e32 v239, 0xffff0000, v124
	v_pk_mul_f32 v[138:139], v[138:139], v[238:239]
	v_cvt_pk_bf16_f32 v124, v138, v139
	v_pk_mul_f32 v[140:141], v[140:141], v[158:159] op_sel_hi:[1,0]
	v_lshlrev_b32_e32 v238, 16, v125
	v_and_b32_e32 v239, 0xffff0000, v125
	v_pk_mul_f32 v[140:141], v[140:141], v[238:239]
	v_cvt_pk_bf16_f32 v125, v140, v141
	v_pk_mul_f32 v[142:143], v[142:143], v[158:159] op_sel_hi:[1,0]
	v_lshlrev_b32_e32 v238, 16, v126
	v_and_b32_e32 v239, 0xffff0000, v126
	v_pk_mul_f32 v[142:143], v[142:143], v[238:239]
	v_cvt_pk_bf16_f32 v126, v142, v143
	v_pk_mul_f32 v[144:145], v[144:145], v[158:159] op_sel_hi:[1,0]
	v_lshlrev_b32_e32 v238, 16, v127
	v_and_b32_e32 v239, 0xffff0000, v127
	v_pk_mul_f32 v[144:145], v[144:145], v[238:239]
	v_cvt_pk_bf16_f32 v127, v144, v145
	global_store_dwordx4 v[162:163], v[124:127], off offset:128
	v_pk_mul_f32 v[146:147], v[146:147], v[158:159] op_sel_hi:[1,0]
	v_lshlrev_b32_e32 v238, 16, v110
	v_and_b32_e32 v239, 0xffff0000, v110
	v_pk_mul_f32 v[146:147], v[146:147], v[238:239]
	v_cvt_pk_bf16_f32 v110, v146, v147
	v_pk_mul_f32 v[148:149], v[148:149], v[158:159] op_sel_hi:[1,0]
	v_lshlrev_b32_e32 v238, 16, v111
	v_and_b32_e32 v239, 0xffff0000, v111
	v_pk_mul_f32 v[148:149], v[148:149], v[238:239]
	v_cvt_pk_bf16_f32 v111, v148, v149
	v_pk_mul_f32 v[150:151], v[150:151], v[158:159] op_sel_hi:[1,0]
	v_lshlrev_b32_e32 v238, 16, v112
	v_and_b32_e32 v239, 0xffff0000, v112
	v_pk_mul_f32 v[150:151], v[150:151], v[238:239]
	v_cvt_pk_bf16_f32 v112, v150, v151
	v_pk_mul_f32 v[152:153], v[152:153], v[158:159] op_sel_hi:[1,0]
	v_lshlrev_b32_e32 v238, 16, v113
	v_and_b32_e32 v239, 0xffff0000, v113
	v_pk_mul_f32 v[152:153], v[152:153], v[238:239]
	v_cvt_pk_bf16_f32 v113, v152, v153
	global_store_dwordx4 v[162:163], v[110:113], off offset:256
	v_pk_mul_f32 v[154:155], v[154:155], v[158:159] op_sel_hi:[1,0]
	v_lshlrev_b32_e32 v238, 16, v88
	v_and_b32_e32 v239, 0xffff0000, v88
	v_pk_mul_f32 v[154:155], v[154:155], v[238:239]
	v_cvt_pk_bf16_f32 v88, v154, v155
	v_pk_mul_f32 v[156:157], v[156:157], v[158:159] op_sel_hi:[1,0]
	v_lshlrev_b32_e32 v238, 16, v89
	v_and_b32_e32 v239, 0xffff0000, v89
	v_pk_mul_f32 v[156:157], v[156:157], v[238:239]
	v_cvt_pk_bf16_f32 v89, v156, v157
	v_pk_mul_f32 v[166:167], v[166:167], v[158:159] op_sel_hi:[1,0]
	v_lshlrev_b32_e32 v238, 16, v116
	v_and_b32_e32 v239, 0xffff0000, v116
	v_pk_mul_f32 v[166:167], v[166:167], v[238:239]
	v_cvt_pk_bf16_f32 v116, v166, v167
	v_pk_mul_f32 v[168:169], v[168:169], v[158:159] op_sel_hi:[1,0]
	v_lshlrev_b32_e32 v238, 16, v117
	v_and_b32_e32 v239, 0xffff0000, v117
	v_pk_mul_f32 v[168:169], v[168:169], v[238:239]
	v_cvt_pk_bf16_f32 v117, v168, v169
	global_store_dwordx2 v[162:163], v[88:89], off offset:384
	global_store_dwordx2 v[162:163], v[116:117], off offset:392
	s_waitcnt vmcnt(33)
	v_add_u32_e32 v238, s10, v217
	v_ashrrev_i32_e32 v239, 31, v238
	v_lshlrev_b64 v[238:239], 13, v[238:239]
	v_lshl_add_u64 v[238:239], v[78:79], 0, v[238:239]
	global_load_dwordx4 v[120:123], v[238:239], off
	global_load_dwordx4 v[124:127], v[238:239], off offset:128
	global_load_dwordx4 v[110:113], v[238:239], off offset:256
	global_load_dwordx2 v[88:89], v[238:239], off offset:384
	global_load_dwordx2 v[116:117], v[238:239], off offset:392
	s_sub_i32 s10, s17, s10
	s_cmp_gt_i32 s10, 31
	s_cbranch_scc1 .LBB0_307
	s_min_i32 s10, s10, 32
	v_add_f32_e32 v130, 0, v68
	v_cmp_gt_i32_e32 vcc, s10, v176
	v_cmp_gt_i32_e64 s[0:1], s10, v40
	v_and_b32_e32 v133, 0xffff0000, v215
	v_cndmask_b32_e32 v144, 0, v130, vcc
	v_add_f32_e32 v130, 0, v69
	v_cndmask_b32_e32 v143, 0, v130, vcc
	v_lshlrev_b32_e32 v130, 16, v201
	v_cndmask_b32_e32 v141, 0, v130, vcc
	v_and_b32_e32 v130, 0xffff0000, v201
	v_cndmask_b32_e32 v169, 0, v130, vcc
	v_cmp_gt_i32_e32 vcc, s10, v1
	v_lshlrev_b32_e32 v132, 16, v202
	v_cndmask_b32_e64 v138, 0, v132, s[0:1]
	v_cndmask_b32_e32 v130, 0, v104, vcc
	v_add_f32_e32 v142, v144, v130
	v_lshlrev_b32_e32 v130, 16, v215
	v_cndmask_b32_e32 v140, 0, v130, vcc
	v_cndmask_b32_e32 v131, 0, v105, vcc
	v_cndmask_b32_e64 v130, 0, v76, s[0:1]
	v_pk_add_f32 v[146:147], v[130:131], v[142:143]
	v_cndmask_b32_e64 v130, 0, v77, s[0:1]
	v_add_f32_e32 v241, v130, v147
	v_cndmask_b32_e32 v139, 0, v133, vcc
	v_and_b32_e32 v130, 0xffff0000, v202
	v_cmp_gt_i32_e32 vcc, s10, v3
	v_cndmask_b32_e64 v166, 0, v130, s[0:1]
	v_and_b32_e32 v131, 0xffff0000, v197
	v_cndmask_b32_e32 v130, 0, v72, vcc
	v_add_f32_e32 v239, v130, v146
	v_cndmask_b32_e32 v130, 0, v73, vcc
	v_add_f32_e32 v240, v130, v241
	v_lshlrev_b32_e32 v130, 16, v200
	v_cndmask_b32_e32 v135, 0, v130, vcc
	v_and_b32_e32 v130, 0xffff0000, v200
	v_cndmask_b32_e32 v159, 0, v130, vcc
	v_cmp_gt_i32_e32 vcc, s10, v43
	v_cmp_gt_i32_e64 s[0:1], s10, v42
	v_and_b32_e32 v133, 0xffff0000, v196
	v_cndmask_b32_e32 v130, 0, v70, vcc
	v_add_f32_e32 v173, v130, v239
	v_cndmask_b32_e32 v130, 0, v71, vcc
	v_add_f32_e32 v238, v130, v240
	v_lshlrev_b32_e32 v130, 16, v197
	v_cndmask_b32_e32 v134, 0, v130, vcc
	v_lshlrev_b32_e32 v130, 16, v198
	v_cndmask_b32_e64 v132, 0, v62, s[0:1]
	v_cndmask_b32_e32 v137, 0, v131, vcc
	v_cndmask_b32_e64 v136, 0, v130, s[0:1]
	v_and_b32_e32 v130, 0xffff0000, v198
	v_cmp_gt_i32_e32 vcc, s10, v45
	v_add_f32_e32 v171, v132, v173
	v_cndmask_b32_e64 v132, 0, v63, s[0:1]
	v_cndmask_b32_e64 v131, 0, v130, s[0:1]
	v_cndmask_b32_e32 v130, 0, v66, vcc
	v_add_f32_e32 v172, v132, v238
	v_add_f32_e32 v168, v130, v171
	v_cndmask_b32_e32 v130, 0, v67, vcc
	v_cmp_gt_i32_e64 s[0:1], s10, v44
	v_add_f32_e32 v170, v130, v172
	v_lshlrev_b32_e32 v130, 16, v196
	v_cndmask_b32_e64 v148, 0, v65, s[0:1]
	v_lshlrev_b32_e32 v132, 16, v225
	v_cndmask_b32_e64 v145, 0, v64, s[0:1]
	v_add_f32_e32 v167, v148, v170
	v_and_b32_e32 v148, 0xffff0000, v225
	v_cndmask_b32_e32 v130, 0, v130, vcc
	v_add_f32_e32 v145, v145, v168
	v_cndmask_b32_e32 v133, 0, v133, vcc
	v_cndmask_b32_e64 v132, 0, v132, s[0:1]
	v_cndmask_b32_e64 v158, 0, v148, s[0:1]
	s_mov_b64 s[0:1], 0
